# attention step loops: waves 4-7 delayed by s_sleep 8 after each step barrier (stagger SIMD-mate waves)
# speedup vs baseline: 1.0029x; 1.0029x over previous
; #define LAS __attribute__((address_space(3)))
; template <bool MOBA>
; __device__ __forceinline__ void attn_unit(unsigned char* lds, LAS unsigned char* lds3, const Params& p, int b, int h, int qb) {
;     int tid_ = threadIdx.x; asm volatile("" : "+v"(tid_)); const int tid = tid_, lane = tid & 63, w = __builtin_amdgcn_readfirstlane(tid >> 6), fr = lane & 15, fq = lane >> 4;
;     const bf16_t* Qg = (const bf16_t*)(p.ws + WS_R1); const bf16_t* Kg = Qg + (size_t)MROWS * DM; const bf16_t* Vg = Kg + (size_t)MROWS * DM;
;     bf16_t* Og = (bf16_t*)(p.ws + WS_R2);
;     const int hcol = (MOBA ? 8 + h : h) * 64; const size_t rowbase = (size_t)b * SEQ;
;     LAS bf16_t* Ks = (LAS bf16_t*)lds3; LAS bf16_t* Vt = (LAS bf16_t*)(lds3 + 36864);
;     LAS float* Fs = (LAS float*)(lds3 + 73728); LAS float* kms = Fs; LAS float* tbl = (LAS float*)(lds3 + 73728 + 4096); LAS unsigned* sel = (LAS unsigned*)(lds3 + 73728 + 4096 + 512);
; __device__ __forceinline__ void phase_attn(const Params& p, unsigned char* lds, LAS unsigned char* lds3) {
;     for (int u = blockIdx.x; u < 2048; u += gridDim.x) {
;         const int bx = u & 255, i = u >> 8; const int wv = (bx & 7) * 32 + (bx >> 3);
;         const int combo = wv >> 2, quarter = wv & 3; const int k = i & 3;
;         const int b = combo >> 3, h = ((combo & 7) + 2 * k + (i >> 2)) & 7;
;         const int qb = (k == 0) ? quarter : (k == 1) ? 15 - quarter : (k == 2) ? 7 - quarter : 8 + quarter;
;         if (i < 4) attn_unit<false>(lds, lds3, p, b, h, qb); else attn_unit<true>(lds, lds3, p, b, h, qb);
.LBB0_356:
	s_andn2_b64 vcc, exec, s[0:1]
	s_cbranch_vccnz .LBB0_617
	v_readfirstlane_b32 s100, v174
	s_nop 3
	s_cmp_ge_u32 s100, 0x100
	s_cselect_b32 s101, 1, 0
	v_writelane_b32 v255, s3, 15
	s_load_dwordx2 s[2:3], s[86:87], 0x90
	v_writelane_b32 v255, s90, 16
	v_writelane_b32 v255, s69, 17
	v_writelane_b32 v255, s68, 18
	s_waitcnt lgkmcnt(0)
	v_writelane_b32 v255, s2, 19
	s_nop 1
	v_writelane_b32 v255, s3, 20
	v_readlane_b32 s2, v254, 11
	v_readlane_b32 s3, v254, 12
	s_andn2_b64 vcc, exec, s[2:3]
	s_cbranch_vccnz .LBB0_555
	v_readlane_b32 s2, v255, 19
	v_readlane_b32 s3, v255, 20
	s_add_u32 s4, s2, 0x13d00000
	s_addc_u32 s5, s3, 0
	s_add_u32 s50, s2, 0x17d00000
	s_addc_u32 s51, s3, 0
	s_add_u32 s52, s2, 0xfd00000
	v_writelane_b32 v255, s4, 21
	s_addc_u32 s53, s3, 0
	s_load_dwordx2 s[0:1], s[86:87], 0x60
	v_writelane_b32 v255, s5, 22
	s_add_u32 s4, s2, 0x64c0000
	v_writelane_b32 v255, s4, 23
	s_addc_u32 s4, s3, 0
	v_writelane_b32 v255, s4, 24
	s_add_u32 s4, s2, 0x6400000
	v_writelane_b32 v255, s4, 25
	s_addc_u32 s4, s3, 0
	s_add_u32 s80, s2, 0xa500000
	s_addc_u32 s81, s3, 0
	v_writelane_b32 v255, s4, 26
	s_add_u32 s4, s2, 0x6300000
	v_writelane_b32 v255, s4, 27
	s_addc_u32 s4, s3, 0
	s_add_u32 s2, s2, 0x13cc0400
	v_writelane_b32 v255, s4, 28
	s_addc_u32 s3, s3, 0
	v_writelane_b32 v255, s2, 29
	s_mov_b32 s95, s73
	s_nop 0
	v_writelane_b32 v255, s3, 30
	v_writelane_b32 v255, s88, 31
	s_mov_b32 s2, s73
	s_nop 0
	v_writelane_b32 v255, s89, 32
	v_writelane_b32 v255, s52, 33
	s_nop 1
	v_writelane_b32 v255, s53, 34
	v_writelane_b32 v255, s50, 35
	s_nop 1
	v_writelane_b32 v255, s51, 36
	s_branch .LBB0_361

; #define LAS __attribute__((address_space(3)))
; #define ATT_STORE(buf) do { ATT_STORE1((buf) * 2, kreg[0], vreg[0]); ATT_STORE1((buf) * 2 + 1, kreg[1], vreg[1]); } while (0)
; template <bool MOBA>
; __device__ __forceinline__ void attn_unit(unsigned char* lds, LAS unsigned char* lds3, const Params& p, int b, int h, int qb) {
;     ...
;         if (st + 1 < NT / 2) ATT_STORE(buf ^ 1);
;         if (!MOBA) { if (lane == 0) dflag[(st & 1) * 8 + w] = wdone ? 1u : 0u; }
;         __syncthreads();
;         if (!MOBA) { const u32x4 fa = *(const LAS u32x4*)(lds3 + 73728 + 16384 + 2048 + 512 + (st & 1) * 32), fb = *(const LAS u32x4*)(lds3 + 73728 + 16384 + 2048 + 512 + (st & 1) * 32 + 16);
;             if ((fa[0] & fa[1] & fa[2] & fa[3] & fb[0] & fb[1] & fb[2] & fb[3]) != 0u) break; }
;     }
.LBB0_461:
	s_cmp_eq_u32 s101, 0
	s_cbranch_scc1 .Lmoba_nosl
	s_sleep 8
